# stack + non-temporal stores for the dilated-attention partial outputs
# baseline (speedup 1.0000x reference)
.LBB0_847:
	ds_read_b128 v[32:35], v239 offset:18432
	ds_read_b128 v[48:51], v239 offset:18464
	ds_read_b128 v[52:55], v239 offset:18496
	ds_read_b128 v[56:59], v239 offset:18528
	v_cmp_lt_i32_e32 vcc, v243, v244
	s_waitcnt vmcnt(3) lgkmcnt(3)
	v_mfma_f32_32x32x16_bf16 v[32:47], v[32:35], v[128:131], 0
	v_add_u32_e32 v132, s86, v164
	s_add_i32 s33, s33, s83
	s_waitcnt vmcnt(2) lgkmcnt(2)
	v_mfma_f32_32x32x16_bf16 v[32:47], v[48:51], v[124:127], v[32:47]
	s_waitcnt vmcnt(1) lgkmcnt(1)
	v_mfma_f32_32x32x16_bf16 v[32:47], v[52:55], v[116:119], v[32:47]
	s_waitcnt vmcnt(0) lgkmcnt(0)
	v_mfma_f32_32x32x16_bf16 v[32:47], v[56:59], v[120:123], v[32:47]
	ds_read_b128 v[60:63], v216
	ds_read_b128 v[56:59], v216 offset:25088
	ds_read_b128 v[48:51], v217
	ds_read_b128 v[52:55], v217 offset:25088
	s_nop 7
	v_cndmask_b32_e64 v116, v32, v240, s[46:47]
	v_cndmask_b32_e64 v116, v116, v32, s[4:5]
	v_cndmask_b32_e64 v117, v240, v33, s[4:5]
	v_cndmask_b32_e64 v34, v34, v240, s[48:49]
	v_cndmask_b32_e64 v35, v35, v240, s[50:51]
	v_max3_f32 v32, v116, s84, v117
	v_cndmask_b32_e64 v36, v36, v240, s[52:53]
	v_cndmask_b32_e64 v37, v37, v240, s[54:55]
	v_max3_f32 v32, v32, v34, v35
	v_cndmask_b32_e64 v38, v38, v240, s[56:57]
	v_cndmask_b32_e64 v39, v39, v240, s[58:59]
	v_max3_f32 v32, v32, v36, v37
	v_cndmask_b32_e64 v40, v40, v240, s[60:61]
	v_cndmask_b32_e64 v41, v41, v240, s[62:63]
	v_max3_f32 v32, v32, v38, v39
	v_cndmask_b32_e64 v42, v42, v240, s[64:65]
	v_cndmask_b32_e64 v43, v43, v240, s[66:67]
	v_max3_f32 v32, v32, v40, v41
	v_cndmask_b32_e64 v44, v44, v240, s[68:69]
	v_cndmask_b32_e64 v45, v45, v240, s[70:71]
	v_max3_f32 v32, v32, v42, v43
	v_cndmask_b32_e64 v46, v46, v240, s[72:73]
	v_cndmask_b32_e64 v47, v47, v240, s[74:75]
	v_max3_f32 v32, v32, v44, v45
	v_cndmask_b32_e32 v33, v133, v243, vcc
	v_max3_f32 v32, v32, v46, v47
	v_lshlrev_b32_e32 v118, 2, v33
	ds_bpermute_b32 v33, v118, v32
	s_waitcnt lgkmcnt(0)
	v_max3_f32 v33, v98, v32, v33
	v_sub_f32_e32 v34, v34, v33
	v_sub_f32_e32 v32, v98, v33
	v_sub_f32_e32 v98, v116, v33
	v_sub_f32_e32 v116, v117, v33
	v_exp_f32_e32 v117, v34
	v_sub_f32_e32 v34, v35, v33
	v_exp_f32_e32 v119, v34
	v_sub_f32_e32 v34, v36, v33
	v_exp_f32_e32 v120, v34
	v_sub_f32_e32 v34, v37, v33
	v_exp_f32_e32 v121, v34
	v_sub_f32_e32 v34, v38, v33
	v_exp_f32_e32 v38, v34
	v_sub_f32_e32 v34, v39, v33
	v_exp_f32_e32 v39, v34
	v_sub_f32_e32 v34, v40, v33
	v_exp_f32_e32 v40, v34
	v_sub_f32_e32 v34, v41, v33
	v_exp_f32_e32 v41, v34
	v_sub_f32_e32 v34, v42, v33
	v_exp_f32_e32 v42, v34
	v_sub_f32_e32 v34, v43, v33
	v_exp_f32_e32 v32, v32
	v_exp_f32_e32 v98, v98
	v_exp_f32_e32 v116, v116
	v_exp_f32_e32 v43, v34
	v_sub_f32_e32 v34, v44, v33
	v_exp_f32_e32 v44, v34
	v_sub_f32_e32 v34, v45, v33
	v_exp_f32_e32 v45, v34
	v_sub_f32_e32 v34, v46, v33
	v_exp_f32_e32 v46, v34
	v_sub_f32_e32 v34, v47, v33
	v_exp_f32_e32 v47, v34
	v_cvt_pk_bf16_f32 v34, v98, v116
	v_fmac_f32_e32 v98, v97, v32
	v_pk_mul_f32 v[16:17], v[16:17], v[32:33] op_sel_hi:[1,0]
	v_pk_mul_f32 v[0:1], v[0:1], v[32:33] op_sel_hi:[1,0]
	v_pk_mul_f32 v[18:19], v[18:19], v[32:33] op_sel_hi:[1,0]
	v_pk_mul_f32 v[2:3], v[2:3], v[32:33] op_sel_hi:[1,0]
	v_pk_mul_f32 v[20:21], v[20:21], v[32:33] op_sel_hi:[1,0]
	v_pk_mul_f32 v[4:5], v[4:5], v[32:33] op_sel_hi:[1,0]
	v_pk_mul_f32 v[22:23], v[22:23], v[32:33] op_sel_hi:[1,0]
	v_pk_mul_f32 v[6:7], v[6:7], v[32:33] op_sel_hi:[1,0]
	v_pk_mul_f32 v[24:25], v[24:25], v[32:33] op_sel_hi:[1,0]
	v_pk_mul_f32 v[8:9], v[8:9], v[32:33] op_sel_hi:[1,0]
	v_pk_mul_f32 v[26:27], v[26:27], v[32:33] op_sel_hi:[1,0]
	v_pk_mul_f32 v[10:11], v[10:11], v[32:33] op_sel_hi:[1,0]
	v_pk_mul_f32 v[28:29], v[28:29], v[32:33] op_sel_hi:[1,0]
	v_pk_mul_f32 v[12:13], v[12:13], v[32:33] op_sel_hi:[1,0]
	v_pk_mul_f32 v[30:31], v[30:31], v[32:33] op_sel_hi:[1,0]
	v_pk_mul_f32 v[14:15], v[14:15], v[32:33] op_sel_hi:[1,0]
	v_add_f32_e32 v32, v116, v98
	v_add_f32_e32 v32, v117, v32
	v_add_f32_e32 v32, v119, v32
	v_add_f32_e32 v32, v120, v32
	v_add_f32_e32 v32, v121, v32
	v_add_f32_e32 v32, v38, v32
	v_cvt_pk_bf16_f32 v35, v117, v119
	v_cvt_pk_bf16_f32 v36, v120, v121
	v_cvt_pk_bf16_f32 v37, v38, v39
	v_add_f32_e32 v32, v39, v32
	v_add_f32_e32 v32, v40, v32
	v_mfma_f32_32x32x16_bf16 v[16:31], v[60:63], v[34:37], v[16:31]
	v_add_f32_e32 v32, v41, v32
	v_add_f32_e32 v32, v42, v32
	v_add_f32_e32 v32, v43, v32
	v_add_f32_e32 v32, v44, v32
	v_add_f32_e32 v32, v45, v32
	v_add_f32_e32 v32, v46, v32
	v_add_f32_e32 v32, v47, v32
	v_mfma_f32_32x32x16_bf16 v[0:15], v[56:59], v[34:37], v[0:15]
	v_cvt_pk_bf16_f32 v34, v40, v41
	v_cvt_pk_bf16_f32 v35, v42, v43
	v_cvt_pk_bf16_f32 v36, v44, v45
	v_cvt_pk_bf16_f32 v37, v46, v47
	s_nop 1
	v_mfma_f32_32x32x16_bf16 v[16:31], v[48:51], v[34:37], v[16:31]
	v_mfma_f32_32x32x16_bf16 v[0:15], v[52:55], v[34:37], v[0:15]
	ds_bpermute_b32 v34, v118, v32
	s_waitcnt lgkmcnt(0)
	v_add_f32_e32 v34, v32, v34
	v_div_scale_f32 v32, s[2:3], v34, v34, 1.0
	v_rcp_f32_e32 v35, v32
	s_lshr_b32 s2, 0x2000, s31
	s_add_i32 s2, s2, -1
	v_fma_f32 v36, -v32, v35, 1.0
	v_fmac_f32_e32 v35, v36, v35
	v_div_scale_f32 v36, vcc, 1.0, v34, 1.0
	v_mul_f32_e32 v37, v36, v35
	v_fma_f32 v38, -v32, v37, v36
	v_fmac_f32_e32 v37, v38, v35
	v_fma_f32 v32, -v32, v37, v36
	v_div_fmas_f32 v32, v32, v35, v37
	v_div_fixup_f32 v32, v32, v34, 1.0
	v_pk_mul_f32 v[16:17], v[16:17], v[32:33] op_sel_hi:[1,0]
	v_pk_mul_f32 v[0:1], v[0:1], v[32:33] op_sel_hi:[1,0]
	v_pk_mul_f32 v[18:19], v[18:19], v[32:33] op_sel_hi:[1,0]
	v_pk_mul_f32 v[2:3], v[2:3], v[32:33] op_sel_hi:[1,0]
	v_pk_mul_f32 v[20:21], v[20:21], v[32:33] op_sel_hi:[1,0]
	v_pk_mul_f32 v[4:5], v[4:5], v[32:33] op_sel_hi:[1,0]
	v_pk_mul_f32 v[22:23], v[22:23], v[32:33] op_sel_hi:[1,0]
	v_pk_mul_f32 v[6:7], v[6:7], v[32:33] op_sel_hi:[1,0]
	v_pk_mul_f32 v[24:25], v[24:25], v[32:33] op_sel_hi:[1,0]
	v_pk_mul_f32 v[8:9], v[8:9], v[32:33] op_sel_hi:[1,0]
	v_pk_mul_f32 v[26:27], v[26:27], v[32:33] op_sel_hi:[1,0]
	v_pk_mul_f32 v[10:11], v[10:11], v[32:33] op_sel_hi:[1,0]
	v_pk_mul_f32 v[28:29], v[28:29], v[32:33] op_sel_hi:[1,0]
	v_pk_mul_f32 v[12:13], v[12:13], v[32:33] op_sel_hi:[1,0]
	v_pk_mul_f32 v[30:31], v[30:31], v[32:33] op_sel_hi:[1,0]
	v_pk_mul_f32 v[14:15], v[14:15], v[32:33] op_sel_hi:[1,0]
	v_log_f32_e32 v32, v34
	v_and_b32_e32 v34, s2, v132
	s_sub_i32 s2, 13, s31
	v_lshlrev_b32_e32 v34, s31, v34
	v_lshrrev_b32_e32 v35, s2, v132
	v_cvt_pk_bf16_f32 v0, v0, v1
	v_cvt_pk_bf16_f32 v1, v2, v3
	v_cvt_pk_bf16_f32 v3, v6, v7
	v_or_b32_e32 v6, v220, v99
	v_or_b32_e32 v34, v34, v35
	v_lshlrev_b32_e32 v6, 2, v6
	ds_bpermute_b32 v6, v6, v34
	v_cvt_pk_bf16_f32 v16, v16, v17
	v_cvt_pk_bf16_f32 v17, v18, v19
	v_cvt_pk_bf16_f32 v18, v20, v21
	v_cvt_pk_bf16_f32 v19, v22, v23
	s_waitcnt lgkmcnt(0)
	v_ashrrev_i32_e32 v7, 31, v6
	ds_write2_b64 v237, v[16:17], v[18:19] offset1:2
	v_cvt_pk_bf16_f32 v16, v24, v25
	v_cvt_pk_bf16_f32 v17, v26, v27
	v_cvt_pk_bf16_f32 v18, v28, v29
	v_cvt_pk_bf16_f32 v19, v30, v31
	v_cvt_pk_bf16_f32 v2, v4, v5
	v_lshl_add_u64 v[4:5], s[76:77], 1, v[174:175]
	v_lshl_add_u64 v[6:7], s[34:35], 0, v[6:7]
	ds_write2_b64 v237, v[16:17], v[18:19] offset0:4 offset1:6
	ds_write2_b64 v237, v[0:1], v[2:3] offset0:8 offset1:10
	v_cvt_pk_bf16_f32 v0, v8, v9
	v_mad_u64_u32 v[8:9], s[2:3], v6, s82, v[4:5]
	v_or_b32_e32 v6, v221, v99
	v_cvt_pk_bf16_f32 v1, v10, v11
	v_cvt_pk_bf16_f32 v2, v12, v13
	v_cvt_pk_bf16_f32 v3, v14, v15
	v_lshlrev_b32_e32 v6, 2, v6
	ds_write2_b64 v237, v[0:1], v[2:3] offset0:12 offset1:14
	ds_bpermute_b32 v6, v6, v34
	s_waitcnt lgkmcnt(0)
	v_add_u32_e32 v0, v218, v219
	ds_read_b128 v[0:3], v0
	v_mad_i32_i24 v9, v7, s82, v9
	s_waitcnt lgkmcnt(1)
	v_ashrrev_i32_e32 v7, 31, v6
	v_lshl_add_u64 v[6:7], s[34:35], 0, v[6:7]
	v_ashrrev_i32_e32 v35, 31, v34
	s_waitcnt lgkmcnt(0)
	global_store_dwordx4 v[8:9], v[0:3], off nt
	v_mad_u64_u32 v[8:9], s[2:3], v6, s82, v[4:5]
	v_or_b32_e32 v6, v222, v99
	v_lshlrev_b32_e32 v6, 2, v6
	ds_bpermute_b32 v6, v6, v34
	ds_read_b128 v[0:3], v238
	v_mad_i32_i24 v9, v7, s82, v9
	s_ashr_i32 s31, s30, 31
	s_and_b64 vcc, exec, s[36:37]
	s_waitcnt lgkmcnt(1)
	v_ashrrev_i32_e32 v7, 31, v6
	v_lshl_add_u64 v[6:7], s[34:35], 0, v[6:7]
	s_waitcnt lgkmcnt(0)
	global_store_dwordx4 v[8:9], v[0:3], off nt
	v_mad_u64_u32 v[8:9], s[2:3], v6, s82, v[4:5]
	v_or_b32_e32 v6, v223, v99
	ds_read_b128 v[0:3], v238 offset:1152
	v_lshlrev_b32_e32 v6, 2, v6
	ds_bpermute_b32 v6, v6, v34
	v_mad_i32_i24 v9, v7, s82, v9
	s_waitcnt lgkmcnt(1)
	global_store_dwordx4 v[8:9], v[0:3], off nt
	ds_read_b128 v[0:3], v238 offset:2304
	s_waitcnt lgkmcnt(1)
	v_ashrrev_i32_e32 v7, 31, v6
	v_lshl_add_u64 v[6:7], s[34:35], 0, v[6:7]
	v_mad_u64_u32 v[4:5], s[2:3], v6, s82, v[4:5]
	v_mad_i32_i24 v5, v7, s82, v5
	s_waitcnt lgkmcnt(0)
	global_store_dwordx4 v[4:5], v[0:3], off nt
	v_add_f32_e32 v4, v33, v32
	s_nop 0
	v_lshl_add_u64 v[0:1], s[34:35], 0, v[34:35]
	v_mad_u64_u32 v[2:3], s[2:3], v0, 48, s[28:29]
	v_mad_i32_i24 v3, v1, 48, v3
	v_lshl_add_u64 v[0:1], s[30:31], 2, v[2:3]
	global_store_dword v[0:1], v4, off
	s_cbranch_vccnz .LBB0_883
